# up-projection epilogue: every 8-byte instruction 8-byte aligned (a few VOP1/VOP2 in VOP3 encoding, paired nops)
# baseline (speedup 1.0000x reference)
.LBB0_382:
	s_waitcnt vmcnt(0)
	v_lshl_or_b32 v144, s29, 7, v156
	v_lshl_add_u32 v164, s28, 8, v1
	v_ashrrev_i32_e64 v145, 31, v144
	v_mov_b64_e32 v[142:143], s[82:83]
	s_movk_i32 s21, 0x1600
	v_mad_i64_i32 v[146:147], s[28:29], v164, s21, v[142:143]
	v_lshlrev_b64 v[144:145], 1, v[144:145]
	v_lshl_add_u64 v[146:147], v[146:147], 0, v[144:145]
	s_andn2_b64 vcc, exec, s[6:7]
	s_nop 0
	v_cvt_f32_u32_e64 v166, v166
	v_fmamk_f32 v170, v166, 0x34800000, v228
	v_rsq_f32_e64 v166, v170
	v_pk_mul_f32 v[122:123], v[126:127], v[122:123]
	v_pk_mul_f32 v[124:125], v[128:129], v[124:125]
	v_pk_mul_f32 v[114:115], v[118:119], v[114:115]
	v_pk_mul_f32 v[116:117], v[120:121], v[116:117]
	v_mul_f32_e32 v172, 0xbfb8aa3b, v166
	v_pk_mul_f32 v[126:127], v[126:127], v[172:173] op_sel_hi:[1,0]
	v_pk_mul_f32 v[128:129], v[128:129], v[172:173] op_sel_hi:[1,0]
	v_pk_mul_f32 v[118:119], v[118:119], v[172:173] op_sel_hi:[1,0]
	v_pk_mul_f32 v[120:121], v[120:121], v[172:173] op_sel_hi:[1,0]
	v_exp_f32_e32 v126, v126
	v_exp_f32_e32 v127, v127
	v_exp_f32_e32 v128, v128
	v_exp_f32_e32 v129, v129
	v_exp_f32_e32 v118, v118
	v_exp_f32_e32 v119, v119
	v_exp_f32_e32 v120, v120
	v_exp_f32_e32 v121, v121
	v_pk_fma_f32 v[126:127], v[126:127], v[170:171], v[170:171] op_sel_hi:[1,0,0]
	v_pk_fma_f32 v[128:129], v[128:129], v[170:171], v[170:171] op_sel_hi:[1,0,0]
	v_pk_fma_f32 v[118:119], v[118:119], v[170:171], v[170:171] op_sel_hi:[1,0,0]
	v_pk_fma_f32 v[120:121], v[120:121], v[170:171], v[170:171] op_sel_hi:[1,0,0]
	v_rcp_f32_e32 v126, v126
	v_rcp_f32_e32 v127, v127
	v_rcp_f32_e32 v128, v128
	v_rcp_f32_e32 v129, v129
	v_rcp_f32_e32 v118, v118
	v_rcp_f32_e32 v119, v119
	v_rcp_f32_e32 v120, v120
	v_rcp_f32_e32 v121, v121
	v_pk_mul_f32 v[122:123], v[122:123], v[126:127]
	v_pk_mul_f32 v[124:125], v[124:125], v[128:129]
	v_pk_mul_f32 v[118:119], v[114:115], v[118:119]
	v_pk_mul_f32 v[120:121], v[116:117], v[120:121]
	v_cvt_pk_bf16_f32 v114, v122, v123
	v_cvt_pk_bf16_f32 v115, v124, v125
	v_cvt_pk_bf16_f32 v116, v118, v119
	v_cvt_pk_bf16_f32 v117, v120, v121
	global_store_dwordx4 v[146:147], v[114:117], off sc1
	s_nop 0
	s_nop 0
	v_cvt_f32_u32_e64 v165, v165
	v_fmamk_f32 v170, v165, 0x34800000, v228
	v_rsq_f32_e64 v165, v170
	v_pk_mul_f32 v[106:107], v[110:111], v[106:107]
	v_pk_mul_f32 v[108:109], v[112:113], v[108:109]
	v_pk_mul_f32 v[98:99], v[102:103], v[98:99]
	v_pk_mul_f32 v[100:101], v[104:105], v[100:101]
	v_mul_f32_e32 v172, 0xbfb8aa3b, v165
	v_pk_mul_f32 v[110:111], v[110:111], v[172:173] op_sel_hi:[1,0]
	v_pk_mul_f32 v[112:113], v[112:113], v[172:173] op_sel_hi:[1,0]
	v_pk_mul_f32 v[102:103], v[102:103], v[172:173] op_sel_hi:[1,0]
	v_pk_mul_f32 v[104:105], v[104:105], v[172:173] op_sel_hi:[1,0]
	v_exp_f32_e32 v110, v110
	v_exp_f32_e32 v111, v111
	v_exp_f32_e32 v112, v112
	v_exp_f32_e32 v113, v113
	v_exp_f32_e32 v102, v102
	v_exp_f32_e32 v103, v103
	v_exp_f32_e32 v104, v104
	v_exp_f32_e32 v105, v105
	v_or_b32_e64 v114, 16, v164
	v_mad_i64_i32 v[114:115], s[28:29], v114, s21, v[142:143]
	v_lshl_add_u64 v[114:115], v[114:115], 0, v[144:145]
	v_pk_fma_f32 v[110:111], v[110:111], v[170:171], v[170:171] op_sel_hi:[1,0,0]
	v_pk_fma_f32 v[112:113], v[112:113], v[170:171], v[170:171] op_sel_hi:[1,0,0]
	v_pk_fma_f32 v[102:103], v[102:103], v[170:171], v[170:171] op_sel_hi:[1,0,0]
	v_pk_fma_f32 v[104:105], v[104:105], v[170:171], v[170:171] op_sel_hi:[1,0,0]
	v_rcp_f32_e32 v110, v110
	v_rcp_f32_e32 v111, v111
	v_rcp_f32_e32 v112, v112
	v_rcp_f32_e32 v113, v113
	v_rcp_f32_e32 v102, v102
	v_rcp_f32_e32 v103, v103
	v_rcp_f32_e32 v104, v104
	v_rcp_f32_e32 v105, v105
	v_pk_mul_f32 v[106:107], v[106:107], v[110:111]
	v_pk_mul_f32 v[108:109], v[108:109], v[112:113]
	v_pk_mul_f32 v[102:103], v[98:99], v[102:103]
	v_pk_mul_f32 v[104:105], v[100:101], v[104:105]
	v_cvt_pk_bf16_f32 v98, v106, v107
	v_cvt_pk_bf16_f32 v99, v108, v109
	v_cvt_pk_bf16_f32 v100, v102, v103
	v_cvt_pk_bf16_f32 v101, v104, v105
	global_store_dwordx4 v[114:115], v[98:101], off sc1
	s_nop 0
	s_nop 0
	v_cvt_f32_u32_e64 v163, v163
	v_fmamk_f32 v170, v163, 0x34800000, v228
	v_rsq_f32_e64 v163, v170
	v_pk_mul_f32 v[90:91], v[94:95], v[90:91]
	v_pk_mul_f32 v[92:93], v[96:97], v[92:93]
	v_pk_mul_f32 v[82:83], v[86:87], v[82:83]
	v_pk_mul_f32 v[84:85], v[88:89], v[84:85]
	v_mul_f32_e32 v172, 0xbfb8aa3b, v163
	v_pk_mul_f32 v[94:95], v[94:95], v[172:173] op_sel_hi:[1,0]
	v_pk_mul_f32 v[96:97], v[96:97], v[172:173] op_sel_hi:[1,0]
	v_pk_mul_f32 v[86:87], v[86:87], v[172:173] op_sel_hi:[1,0]
	v_pk_mul_f32 v[88:89], v[88:89], v[172:173] op_sel_hi:[1,0]
	v_exp_f32_e32 v94, v94
	v_exp_f32_e32 v95, v95
	v_exp_f32_e32 v96, v96
	v_exp_f32_e32 v97, v97
	v_exp_f32_e32 v86, v86
	v_exp_f32_e32 v87, v87
	v_exp_f32_e32 v88, v88
	v_exp_f32_e32 v89, v89
	v_or_b32_e64 v98, 32, v164
	v_mad_i64_i32 v[98:99], s[28:29], v98, s21, v[142:143]
	v_lshl_add_u64 v[98:99], v[98:99], 0, v[144:145]
	v_pk_fma_f32 v[94:95], v[94:95], v[170:171], v[170:171] op_sel_hi:[1,0,0]
	v_pk_fma_f32 v[96:97], v[96:97], v[170:171], v[170:171] op_sel_hi:[1,0,0]
	v_pk_fma_f32 v[86:87], v[86:87], v[170:171], v[170:171] op_sel_hi:[1,0,0]
	v_pk_fma_f32 v[88:89], v[88:89], v[170:171], v[170:171] op_sel_hi:[1,0,0]
	v_rcp_f32_e32 v94, v94
	v_rcp_f32_e32 v95, v95
	v_rcp_f32_e32 v96, v96
	v_rcp_f32_e32 v97, v97
	v_rcp_f32_e32 v86, v86
	v_rcp_f32_e32 v87, v87
	v_rcp_f32_e32 v88, v88
	v_rcp_f32_e32 v89, v89
	v_pk_mul_f32 v[90:91], v[90:91], v[94:95]
	v_pk_mul_f32 v[92:93], v[92:93], v[96:97]
	v_pk_mul_f32 v[86:87], v[82:83], v[86:87]
	v_pk_mul_f32 v[88:89], v[84:85], v[88:89]
	v_cvt_pk_bf16_f32 v82, v90, v91
	v_cvt_pk_bf16_f32 v83, v92, v93
	v_cvt_pk_bf16_f32 v84, v86, v87
	v_cvt_pk_bf16_f32 v85, v88, v89
	global_store_dwordx4 v[98:99], v[82:85], off sc1
	s_nop 0
	s_nop 0
	v_cvt_f32_u32_e64 v162, v162
	v_fmamk_f32 v170, v162, 0x34800000, v228
	v_rsq_f32_e64 v162, v170
	v_pk_mul_f32 v[74:75], v[78:79], v[74:75]
	v_pk_mul_f32 v[76:77], v[80:81], v[76:77]
	v_pk_mul_f32 v[66:67], v[70:71], v[66:67]
	v_pk_mul_f32 v[68:69], v[72:73], v[68:69]
	v_mul_f32_e32 v172, 0xbfb8aa3b, v162
	v_pk_mul_f32 v[78:79], v[78:79], v[172:173] op_sel_hi:[1,0]
	v_pk_mul_f32 v[80:81], v[80:81], v[172:173] op_sel_hi:[1,0]
	v_pk_mul_f32 v[70:71], v[70:71], v[172:173] op_sel_hi:[1,0]
	v_pk_mul_f32 v[72:73], v[72:73], v[172:173] op_sel_hi:[1,0]
	v_exp_f32_e32 v78, v78
	v_exp_f32_e32 v79, v79
	v_exp_f32_e32 v80, v80
	v_exp_f32_e32 v81, v81
	v_exp_f32_e32 v70, v70
	v_exp_f32_e32 v71, v71
	v_exp_f32_e32 v72, v72
	v_exp_f32_e32 v73, v73
	v_or_b32_e64 v82, 48, v164
	v_mad_i64_i32 v[82:83], s[28:29], v82, s21, v[142:143]
	v_lshl_add_u64 v[82:83], v[82:83], 0, v[144:145]
	v_pk_fma_f32 v[78:79], v[78:79], v[170:171], v[170:171] op_sel_hi:[1,0,0]
	v_pk_fma_f32 v[80:81], v[80:81], v[170:171], v[170:171] op_sel_hi:[1,0,0]
	v_pk_fma_f32 v[70:71], v[70:71], v[170:171], v[170:171] op_sel_hi:[1,0,0]
	v_pk_fma_f32 v[72:73], v[72:73], v[170:171], v[170:171] op_sel_hi:[1,0,0]
	v_rcp_f32_e32 v78, v78
	v_rcp_f32_e32 v79, v79
	v_rcp_f32_e32 v80, v80
	v_rcp_f32_e32 v81, v81
	v_rcp_f32_e32 v70, v70
	v_rcp_f32_e32 v71, v71
	v_rcp_f32_e32 v72, v72
	v_rcp_f32_e32 v73, v73
	v_pk_mul_f32 v[74:75], v[74:75], v[78:79]
	v_pk_mul_f32 v[76:77], v[76:77], v[80:81]
	v_pk_mul_f32 v[70:71], v[66:67], v[70:71]
	v_pk_mul_f32 v[72:73], v[68:69], v[72:73]
	v_cvt_pk_bf16_f32 v66, v74, v75
	v_cvt_pk_bf16_f32 v67, v76, v77
	v_cvt_pk_bf16_f32 v68, v70, v71
	v_cvt_pk_bf16_f32 v69, v72, v73
	global_store_dwordx4 v[82:83], v[66:69], off sc1
	s_nop 0
	s_nop 0
	v_cvt_f32_u32_e64 v161, v161
	v_fmamk_f32 v170, v161, 0x34800000, v228
	v_rsq_f32_e64 v161, v170
	v_pk_mul_f32 v[58:59], v[62:63], v[58:59]
	v_pk_mul_f32 v[60:61], v[64:65], v[60:61]
	v_pk_mul_f32 v[50:51], v[54:55], v[50:51]
	v_pk_mul_f32 v[52:53], v[56:57], v[52:53]
	v_mul_f32_e32 v172, 0xbfb8aa3b, v161
	v_pk_mul_f32 v[62:63], v[62:63], v[172:173] op_sel_hi:[1,0]
	v_pk_mul_f32 v[64:65], v[64:65], v[172:173] op_sel_hi:[1,0]
	v_pk_mul_f32 v[54:55], v[54:55], v[172:173] op_sel_hi:[1,0]
	v_pk_mul_f32 v[56:57], v[56:57], v[172:173] op_sel_hi:[1,0]
	v_exp_f32_e32 v62, v62
	v_exp_f32_e32 v63, v63
	v_exp_f32_e32 v64, v64
	v_exp_f32_e32 v65, v65
	v_exp_f32_e32 v54, v54
	v_exp_f32_e32 v55, v55
	v_exp_f32_e32 v56, v56
	v_exp_f32_e32 v57, v57
	v_add_u32_e32 v66, 0x80, v164
	v_mad_i64_i32 v[66:67], s[28:29], v66, s21, v[142:143]
	v_lshl_add_u64 v[66:67], v[66:67], 0, v[144:145]
	v_pk_fma_f32 v[62:63], v[62:63], v[170:171], v[170:171] op_sel_hi:[1,0,0]
	v_pk_fma_f32 v[64:65], v[64:65], v[170:171], v[170:171] op_sel_hi:[1,0,0]
	v_pk_fma_f32 v[54:55], v[54:55], v[170:171], v[170:171] op_sel_hi:[1,0,0]
	v_pk_fma_f32 v[56:57], v[56:57], v[170:171], v[170:171] op_sel_hi:[1,0,0]
	v_rcp_f32_e32 v62, v62
	v_rcp_f32_e32 v63, v63
	v_rcp_f32_e32 v64, v64
	v_rcp_f32_e32 v65, v65
	v_rcp_f32_e32 v54, v54
	v_rcp_f32_e32 v55, v55
	v_rcp_f32_e32 v56, v56
	v_rcp_f32_e32 v57, v57
	v_pk_mul_f32 v[58:59], v[58:59], v[62:63]
	v_pk_mul_f32 v[60:61], v[60:61], v[64:65]
	v_pk_mul_f32 v[54:55], v[50:51], v[54:55]
	v_pk_mul_f32 v[56:57], v[52:53], v[56:57]
	v_cvt_pk_bf16_f32 v50, v58, v59
	v_cvt_pk_bf16_f32 v51, v60, v61
	v_cvt_pk_bf16_f32 v52, v54, v55
	v_cvt_pk_bf16_f32 v53, v56, v57
	global_store_dwordx4 v[66:67], v[50:53], off sc1
	s_nop 0
	s_nop 0
	v_cvt_f32_u32_e64 v160, v160
	v_fmamk_f32 v170, v160, 0x34800000, v228
	v_rsq_f32_e64 v160, v170
	v_pk_mul_f32 v[42:43], v[46:47], v[42:43]
	v_pk_mul_f32 v[44:45], v[48:49], v[44:45]
	v_pk_mul_f32 v[34:35], v[38:39], v[34:35]
	v_pk_mul_f32 v[36:37], v[40:41], v[36:37]
	v_mul_f32_e32 v172, 0xbfb8aa3b, v160
	v_pk_mul_f32 v[46:47], v[46:47], v[172:173] op_sel_hi:[1,0]
	v_pk_mul_f32 v[48:49], v[48:49], v[172:173] op_sel_hi:[1,0]
	v_pk_mul_f32 v[38:39], v[38:39], v[172:173] op_sel_hi:[1,0]
	v_pk_mul_f32 v[40:41], v[40:41], v[172:173] op_sel_hi:[1,0]
	v_exp_f32_e32 v46, v46
	v_exp_f32_e32 v47, v47
	v_exp_f32_e32 v48, v48
	v_exp_f32_e32 v49, v49
	v_exp_f32_e32 v38, v38
	v_exp_f32_e32 v39, v39
	v_exp_f32_e32 v40, v40
	v_exp_f32_e32 v41, v41
	v_add_u32_e32 v50, 0x90, v164
	v_mad_i64_i32 v[50:51], s[28:29], v50, s21, v[142:143]
	v_lshl_add_u64 v[50:51], v[50:51], 0, v[144:145]
	v_pk_fma_f32 v[46:47], v[46:47], v[170:171], v[170:171] op_sel_hi:[1,0,0]
	v_pk_fma_f32 v[48:49], v[48:49], v[170:171], v[170:171] op_sel_hi:[1,0,0]
	v_pk_fma_f32 v[38:39], v[38:39], v[170:171], v[170:171] op_sel_hi:[1,0,0]
	v_pk_fma_f32 v[40:41], v[40:41], v[170:171], v[170:171] op_sel_hi:[1,0,0]
	v_rcp_f32_e32 v46, v46
	v_rcp_f32_e32 v47, v47
	v_rcp_f32_e32 v48, v48
	v_rcp_f32_e32 v49, v49
	v_rcp_f32_e32 v38, v38
	v_rcp_f32_e32 v39, v39
	v_rcp_f32_e32 v40, v40
	v_rcp_f32_e32 v41, v41
	v_pk_mul_f32 v[42:43], v[42:43], v[46:47]
	v_pk_mul_f32 v[44:45], v[44:45], v[48:49]
	v_pk_mul_f32 v[38:39], v[34:35], v[38:39]
	v_pk_mul_f32 v[40:41], v[36:37], v[40:41]
	v_cvt_pk_bf16_f32 v34, v42, v43
	v_cvt_pk_bf16_f32 v35, v44, v45
	v_cvt_pk_bf16_f32 v36, v38, v39
	v_cvt_pk_bf16_f32 v37, v40, v41
	global_store_dwordx4 v[50:51], v[34:37], off sc1
	s_nop 0
	s_nop 0
	v_cvt_f32_u32_e64 v159, v159
	v_fmamk_f32 v170, v159, 0x34800000, v228
	v_rsq_f32_e64 v159, v170
	v_pk_mul_f32 v[26:27], v[30:31], v[26:27]
	v_pk_mul_f32 v[28:29], v[32:33], v[28:29]
	v_pk_mul_f32 v[18:19], v[22:23], v[18:19]
	v_pk_mul_f32 v[20:21], v[24:25], v[20:21]
	v_mul_f32_e32 v172, 0xbfb8aa3b, v159
	v_pk_mul_f32 v[30:31], v[30:31], v[172:173] op_sel_hi:[1,0]
	v_pk_mul_f32 v[32:33], v[32:33], v[172:173] op_sel_hi:[1,0]
	v_pk_mul_f32 v[22:23], v[22:23], v[172:173] op_sel_hi:[1,0]
	v_pk_mul_f32 v[24:25], v[24:25], v[172:173] op_sel_hi:[1,0]
	v_exp_f32_e32 v30, v30
	v_exp_f32_e32 v31, v31
	v_exp_f32_e32 v32, v32
	v_exp_f32_e32 v33, v33
	v_exp_f32_e32 v22, v22
	v_exp_f32_e32 v23, v23
	v_exp_f32_e32 v24, v24
	v_exp_f32_e32 v25, v25
	v_add_u32_e32 v34, 0xa0, v164
	v_mad_i64_i32 v[34:35], s[28:29], v34, s21, v[142:143]
	v_lshl_add_u64 v[34:35], v[34:35], 0, v[144:145]
	v_pk_fma_f32 v[30:31], v[30:31], v[170:171], v[170:171] op_sel_hi:[1,0,0]
	v_pk_fma_f32 v[32:33], v[32:33], v[170:171], v[170:171] op_sel_hi:[1,0,0]
	v_pk_fma_f32 v[22:23], v[22:23], v[170:171], v[170:171] op_sel_hi:[1,0,0]
	v_pk_fma_f32 v[24:25], v[24:25], v[170:171], v[170:171] op_sel_hi:[1,0,0]
	v_rcp_f32_e32 v30, v30
	v_rcp_f32_e32 v31, v31
	v_rcp_f32_e32 v32, v32
	v_rcp_f32_e32 v33, v33
	v_rcp_f32_e32 v22, v22
	v_rcp_f32_e32 v23, v23
	v_rcp_f32_e32 v24, v24
	v_rcp_f32_e32 v25, v25
	v_pk_mul_f32 v[26:27], v[26:27], v[30:31]
	v_pk_mul_f32 v[28:29], v[28:29], v[32:33]
	v_pk_mul_f32 v[22:23], v[18:19], v[22:23]
	v_pk_mul_f32 v[24:25], v[20:21], v[24:25]
	v_cvt_pk_bf16_f32 v18, v26, v27
	v_cvt_pk_bf16_f32 v19, v28, v29
	v_cvt_pk_bf16_f32 v20, v22, v23
	v_cvt_pk_bf16_f32 v21, v24, v25
	global_store_dwordx4 v[34:35], v[18:21], off sc1
	s_nop 0
	s_nop 0
	v_cvt_f32_u32_e64 v158, v158
	v_fmamk_f32 v170, v158, 0x34800000, v228
	v_rsq_f32_e64 v158, v170
	v_pk_mul_f32 v[10:11], v[14:15], v[10:11]
	v_pk_mul_f32 v[12:13], v[16:17], v[12:13]
	v_pk_mul_f32 v[2:3], v[6:7], v[2:3]
	v_pk_mul_f32 v[4:5], v[8:9], v[4:5]
	v_mul_f32_e32 v172, 0xbfb8aa3b, v158
	v_pk_mul_f32 v[14:15], v[14:15], v[172:173] op_sel_hi:[1,0]
	v_pk_mul_f32 v[16:17], v[16:17], v[172:173] op_sel_hi:[1,0]
	v_pk_mul_f32 v[6:7], v[6:7], v[172:173] op_sel_hi:[1,0]
	v_pk_mul_f32 v[8:9], v[8:9], v[172:173] op_sel_hi:[1,0]
	v_exp_f32_e32 v14, v14
	v_exp_f32_e32 v15, v15
	v_exp_f32_e32 v16, v16
	v_exp_f32_e32 v17, v17
	v_exp_f32_e32 v6, v6
	v_exp_f32_e32 v7, v7
	v_exp_f32_e32 v8, v8
	v_exp_f32_e32 v9, v9
	v_add_u32_e32 v18, 0xb0, v164
	v_mad_i64_i32 v[18:19], s[28:29], v18, s21, v[142:143]
	v_lshl_add_u64 v[18:19], v[18:19], 0, v[144:145]
	v_pk_fma_f32 v[14:15], v[14:15], v[170:171], v[170:171] op_sel_hi:[1,0,0]
	v_pk_fma_f32 v[16:17], v[16:17], v[170:171], v[170:171] op_sel_hi:[1,0,0]
	v_pk_fma_f32 v[6:7], v[6:7], v[170:171], v[170:171] op_sel_hi:[1,0,0]
	v_pk_fma_f32 v[8:9], v[8:9], v[170:171], v[170:171] op_sel_hi:[1,0,0]
	v_rcp_f32_e32 v14, v14
	v_rcp_f32_e32 v15, v15
	v_rcp_f32_e32 v16, v16
	v_rcp_f32_e32 v17, v17
	v_rcp_f32_e32 v6, v6
	v_rcp_f32_e32 v7, v7
	v_rcp_f32_e32 v8, v8
	v_rcp_f32_e32 v9, v9
	v_pk_mul_f32 v[10:11], v[10:11], v[14:15]
	v_pk_mul_f32 v[12:13], v[12:13], v[16:17]
	v_pk_mul_f32 v[6:7], v[2:3], v[6:7]
	v_pk_mul_f32 v[8:9], v[4:5], v[8:9]
	v_cvt_pk_bf16_f32 v2, v10, v11
	v_cvt_pk_bf16_f32 v3, v12, v13
	v_cvt_pk_bf16_f32 v4, v6, v7
	v_cvt_pk_bf16_f32 v5, v8, v9
	global_store_dwordx4 v[18:19], v[2:5], off sc1
	s_nop 0
	s_nop 0
	s_mov_b64 s[28:29], -1
	s_cbranch_vccnz .LBB0_359
	s_lshl_b32 s6, s22, 8
	v_add_u32_e32 v2, s6, v1
	v_ashrrev_i32_e32 v3, 31, v2
	v_lshl_add_u64 v[2:3], v[2:3], 2, s[12:13]
	global_load_dword v166, v[2:3], off
	v_add_u32_e32 v2, s6, v148
	v_ashrrev_i32_e32 v3, 31, v2
	v_lshl_add_u64 v[2:3], v[2:3], 2, s[12:13]
	global_load_dword v165, v[2:3], off
	v_add_u32_e32 v2, s6, v149
	v_ashrrev_i32_e32 v3, 31, v2
	v_lshl_add_u64 v[2:3], v[2:3], 2, s[12:13]
	global_load_dword v163, v[2:3], off
	v_add_u32_e32 v2, s6, v150
	v_ashrrev_i32_e32 v3, 31, v2
	v_lshl_add_u64 v[2:3], v[2:3], 2, s[12:13]
	global_load_dword v162, v[2:3], off
	v_add_u32_e32 v2, s6, v151
	v_ashrrev_i32_e32 v3, 31, v2
	v_lshl_add_u64 v[2:3], v[2:3], 2, s[12:13]
	global_load_dword v161, v[2:3], off
	v_add_u32_e32 v2, s6, v152
	v_ashrrev_i32_e32 v3, 31, v2
	v_lshl_add_u64 v[2:3], v[2:3], 2, s[12:13]
	global_load_dword v160, v[2:3], off
	v_add_u32_e32 v2, s6, v153
	v_ashrrev_i32_e32 v3, 31, v2
	v_lshl_add_u64 v[2:3], v[2:3], 2, s[12:13]
	global_load_dword v159, v[2:3], off
	v_add_u32_e32 v2, s6, v154
	v_ashrrev_i32_e32 v3, 31, v2
	v_lshl_add_u64 v[2:3], v[2:3], 2, s[12:13]
	global_load_dword v158, v[2:3], off
	s_andn2_b64 vcc, exec, s[14:15]
	s_cbranch_vccnz .LBB0_358
	s_barrier
	s_branch .LBB0_358

.LBB0_476:
	s_add_i32 s63, s31, 2
	s_add_u32 s38, s28, s36
	s_addc_u32 s39, s29, s37
	s_add_u32 s64, s26, s36
	s_addc_u32 s65, s27, s37
	s_add_i32 s66, 0, 0x10000
	s_cmp_eq_u32 s59, s31
	s_cselect_b32 s39, s9, s39
	s_cselect_b32 s38, s8, s38
	s_cselect_b32 s65, s35, s65
	s_cselect_b32 s64, s34, s64
	s_add_i32 s31, 0, 0x14000
	v_add_u32_e32 v160, s66, v146
	v_add_u32_e32 v176, s31, v146
	ds_read_b128 v[148:151], v160
	ds_read_b128 v[152:155], v160 offset:1024
	ds_read_b128 v[156:159], v160 offset:2048
	ds_read_b128 v[160:163], v160 offset:3072
	ds_read_b128 v[164:167], v176
	ds_read_b128 v[168:171], v176 offset:1024
	ds_read_b128 v[172:175], v176 offset:2048
	ds_read_b128 v[176:179], v176 offset:3072
	v_lshl_add_u64 v[208:209], s[28:29], 0, v[142:143]
	s_add_i32 m0, s51, 0xc000
	ds_read_b128 v[180:183], v147
	ds_read_b128 v[184:187], v147 offset:1024
	ds_read_b128 v[188:191], v147 offset:2048
	ds_read_b128 v[192:195], v147 offset:3072
	ds_read_b128 v[196:199], v147 offset:4096
	ds_read_b128 v[200:203], v147 offset:5120
	ds_read_b128 v[204:207], v147 offset:6144
	ds_read_b128 v[220:223], v147 offset:7168
	global_load_lds_dwordx4 v[208:209], off
	v_lshl_add_u64 v[208:209], s[28:29], 0, v[144:145]
	s_add_i32 m0, s51, 0xe000
	s_nop 0
	global_load_lds_dwordx4 v[208:209], off
	s_nop 0
	s_waitcnt vmcnt(8)
	s_waitcnt lgkmcnt(0)
	s_barrier
	s_waitcnt lgkmcnt(0)
	v_mfma_f32_16x16x32_bf16 v[126:129], v[148:151], v[180:183], v[126:129]
	v_mfma_f32_16x16x32_bf16 v[122:125], v[156:159], v[180:183], v[122:125]
	v_mfma_f32_16x16x32_bf16 v[110:113], v[148:151], v[188:191], v[110:113]
	v_mfma_f32_16x16x32_bf16 v[106:109], v[156:159], v[188:191], v[106:109]
	v_mfma_f32_16x16x32_bf16 v[94:97], v[148:151], v[196:199], v[94:97]
	v_mfma_f32_16x16x32_bf16 v[90:93], v[156:159], v[196:199], v[90:93]
	v_mfma_f32_16x16x32_bf16 v[78:81], v[148:151], v[204:207], v[78:81]
	v_mfma_f32_16x16x32_bf16 v[74:77], v[156:159], v[204:207], v[74:77]
	v_mfma_f32_16x16x32_bf16 v[126:129], v[152:155], v[184:187], v[126:129]
	v_mfma_f32_16x16x32_bf16 v[122:125], v[160:163], v[184:187], v[122:125]
	v_mfma_f32_16x16x32_bf16 v[110:113], v[152:155], v[192:195], v[110:113]
	v_mfma_f32_16x16x32_bf16 v[106:109], v[160:163], v[192:195], v[106:109]
	v_mfma_f32_16x16x32_bf16 v[94:97], v[152:155], v[200:203], v[94:97]
	v_mfma_f32_16x16x32_bf16 v[90:93], v[160:163], v[200:203], v[90:93]
	v_mfma_f32_16x16x32_bf16 v[78:81], v[152:155], v[220:223], v[78:81]
	v_mfma_f32_16x16x32_bf16 v[74:77], v[160:163], v[220:223], v[74:77]
	v_mfma_f32_16x16x32_bf16 v[118:121], v[164:167], v[180:183], v[118:121]
	v_mfma_f32_16x16x32_bf16 v[114:117], v[172:175], v[180:183], v[114:117]
	v_mfma_f32_16x16x32_bf16 v[102:105], v[164:167], v[188:191], v[102:105]
	v_mfma_f32_16x16x32_bf16 v[98:101], v[172:175], v[188:191], v[98:101]
	v_mfma_f32_16x16x32_bf16 v[86:89], v[164:167], v[196:199], v[86:89]
	v_mfma_f32_16x16x32_bf16 v[82:85], v[172:175], v[196:199], v[82:85]
	v_mfma_f32_16x16x32_bf16 v[70:73], v[164:167], v[204:207], v[70:73]
	v_mfma_f32_16x16x32_bf16 v[66:69], v[172:175], v[204:207], v[66:69]
	v_mfma_f32_16x16x32_bf16 v[118:121], v[168:171], v[184:187], v[118:121]
	v_mfma_f32_16x16x32_bf16 v[114:117], v[176:179], v[184:187], v[114:117]
	v_mfma_f32_16x16x32_bf16 v[102:105], v[168:171], v[192:195], v[102:105]
	v_mfma_f32_16x16x32_bf16 v[98:101], v[176:179], v[192:195], v[98:101]
	v_mfma_f32_16x16x32_bf16 v[86:89], v[168:171], v[200:203], v[86:89]
	v_mfma_f32_16x16x32_bf16 v[82:85], v[176:179], v[200:203], v[82:85]
	v_mfma_f32_16x16x32_bf16 v[70:73], v[168:171], v[220:223], v[70:73]
	v_mfma_f32_16x16x32_bf16 v[66:69], v[176:179], v[220:223], v[66:69]
	s_barrier
	s_add_i32 s66, s66, s47
	v_lshl_add_u64 v[208:209], s[64:65], 0, v[132:133]
	s_mov_b32 m0, s66
	ds_read_b128 v[180:183], v147 offset:16384
	ds_read_b128 v[184:187], v147 offset:17408
	ds_read_b128 v[188:191], v147 offset:18432
	ds_read_b128 v[192:195], v147 offset:19456
	ds_read_b128 v[196:199], v147 offset:20480
	ds_read_b128 v[200:203], v147 offset:21504
	ds_read_b128 v[204:207], v147 offset:22528
	ds_read_b128 v[220:223], v147 offset:23552
	global_load_lds_dwordx4 v[208:209], off
	s_add_i32 m0, s66, 0x2000
	v_lshl_add_u64 v[224:225], s[64:65], 0, v[136:137]
	s_add_u32 s64, s64, s45
	s_addc_u32 s65, s65, 0
	s_add_i32 s31, s31, s47
	global_load_lds_dwordx4 v[224:225], off
	v_lshl_add_u64 v[230:231], s[64:65], 0, v[132:133]
	s_mov_b32 m0, s31
	v_lshl_add_u64 v[236:237], s[64:65], 0, v[136:137]
	global_load_lds_dwordx4 v[230:231], off
	s_add_i32 m0, s31, 0x2000
	v_lshl_add_u64 v[238:239], s[38:39], 0, v[130:131]
	global_load_lds_dwordx4 v[236:237], off
	s_mov_b32 m0, s51
	v_lshl_add_u64 v[240:241], s[38:39], 0, v[134:135]
	global_load_lds_dwordx4 v[238:239], off
	s_mov_b32 m0, s52
	s_nop 0
	global_load_lds_dwordx4 v[240:241], off
	s_nop 0
	s_nop 0
	s_nop 0
	s_nop 0
	s_nop 0
	s_nop 0
	s_waitcnt vmcnt(8)
	s_waitcnt lgkmcnt(0)
	s_barrier
	s_waitcnt lgkmcnt(0)
	v_mfma_f32_16x16x32_bf16 v[62:65], v[148:151], v[180:183], v[62:65]
	v_mfma_f32_16x16x32_bf16 v[58:61], v[156:159], v[180:183], v[58:61]
	v_mfma_f32_16x16x32_bf16 v[46:49], v[148:151], v[188:191], v[46:49]
	v_mfma_f32_16x16x32_bf16 v[42:45], v[156:159], v[188:191], v[42:45]
	v_mfma_f32_16x16x32_bf16 v[30:33], v[148:151], v[196:199], v[30:33]
	v_mfma_f32_16x16x32_bf16 v[26:29], v[156:159], v[196:199], v[26:29]
	v_mfma_f32_16x16x32_bf16 v[14:17], v[148:151], v[204:207], v[14:17]
	v_mfma_f32_16x16x32_bf16 v[10:13], v[156:159], v[204:207], v[10:13]
	v_mfma_f32_16x16x32_bf16 v[62:65], v[152:155], v[184:187], v[62:65]
	v_mfma_f32_16x16x32_bf16 v[58:61], v[160:163], v[184:187], v[58:61]
	v_mfma_f32_16x16x32_bf16 v[46:49], v[152:155], v[192:195], v[46:49]
	v_mfma_f32_16x16x32_bf16 v[42:45], v[160:163], v[192:195], v[42:45]
	v_mfma_f32_16x16x32_bf16 v[30:33], v[152:155], v[200:203], v[30:33]
	v_mfma_f32_16x16x32_bf16 v[26:29], v[160:163], v[200:203], v[26:29]
	v_mfma_f32_16x16x32_bf16 v[14:17], v[152:155], v[220:223], v[14:17]
	v_mfma_f32_16x16x32_bf16 v[10:13], v[160:163], v[220:223], v[10:13]
	v_mfma_f32_16x16x32_bf16 v[54:57], v[164:167], v[180:183], v[54:57]
	v_mfma_f32_16x16x32_bf16 v[50:53], v[172:175], v[180:183], v[50:53]
	v_mfma_f32_16x16x32_bf16 v[38:41], v[164:167], v[188:191], v[38:41]
	v_mfma_f32_16x16x32_bf16 v[34:37], v[172:175], v[188:191], v[34:37]
	v_mfma_f32_16x16x32_bf16 v[22:25], v[164:167], v[196:199], v[22:25]
	v_mfma_f32_16x16x32_bf16 v[18:21], v[172:175], v[196:199], v[18:21]
	v_mfma_f32_16x16x32_bf16 v[6:9], v[164:167], v[204:207], v[6:9]
	v_mfma_f32_16x16x32_bf16 v[2:5], v[172:175], v[204:207], v[2:5]
	v_mfma_f32_16x16x32_bf16 v[54:57], v[168:171], v[184:187], v[54:57]
	v_mfma_f32_16x16x32_bf16 v[50:53], v[176:179], v[184:187], v[50:53]
	v_mfma_f32_16x16x32_bf16 v[38:41], v[168:171], v[192:195], v[38:41]
	v_mfma_f32_16x16x32_bf16 v[34:37], v[176:179], v[192:195], v[34:37]
	v_mfma_f32_16x16x32_bf16 v[22:25], v[168:171], v[200:203], v[22:25]
	v_mfma_f32_16x16x32_bf16 v[18:21], v[176:179], v[200:203], v[18:21]
	v_mfma_f32_16x16x32_bf16 v[6:9], v[168:171], v[220:223], v[6:9]
	v_mfma_f32_16x16x32_bf16 v[2:5], v[176:179], v[220:223], v[2:5]
	s_barrier
	s_add_i32 s31, 0, 0x18000
	s_add_i32 s64, 0, 0x1c000
	v_add_u32_e32 v160, s31, v146
	v_add_u32_e32 v176, s64, v146
	ds_read_b128 v[148:151], v160
	ds_read_b128 v[152:155], v160 offset:1024
	ds_read_b128 v[156:159], v160 offset:2048
	ds_read_b128 v[160:163], v160 offset:3072
	ds_read_b128 v[164:167], v176
	ds_read_b128 v[168:171], v176 offset:1024
	ds_read_b128 v[172:175], v176 offset:2048
	ds_read_b128 v[176:179], v176 offset:3072
	s_add_u32 s38, s38, s45
	s_addc_u32 s39, s39, 0
	s_mov_b32 m0, s53
	v_lshl_add_u64 v[242:243], s[38:39], 0, v[130:131]
	ds_read_b128 v[180:183], v147 offset:32768
	ds_read_b128 v[184:187], v147 offset:33792
	ds_read_b128 v[188:191], v147 offset:34816
	ds_read_b128 v[192:195], v147 offset:35840
	ds_read_b128 v[196:199], v147 offset:36864
	ds_read_b128 v[200:203], v147 offset:37888
	ds_read_b128 v[204:207], v147 offset:38912
	ds_read_b128 v[220:223], v147 offset:39936
	global_load_lds_dwordx4 v[242:243], off
	v_lshl_add_u64 v[242:243], s[38:39], 0, v[134:135]
	s_mov_b32 m0, s54
	s_nop 0
	global_load_lds_dwordx4 v[242:243], off
	s_nop 0
	s_nop 0
	s_nop 0
	s_nop 0
	s_nop 0
	s_nop 0
	s_nop 0
	s_nop 0
	s_waitcnt vmcnt(8)
	s_waitcnt lgkmcnt(0)
	s_barrier
	s_waitcnt lgkmcnt(0)
	v_mfma_f32_16x16x32_bf16 v[126:129], v[148:151], v[180:183], v[126:129]
	v_mfma_f32_16x16x32_bf16 v[122:125], v[156:159], v[180:183], v[122:125]
	v_mfma_f32_16x16x32_bf16 v[110:113], v[148:151], v[188:191], v[110:113]
	v_mfma_f32_16x16x32_bf16 v[106:109], v[156:159], v[188:191], v[106:109]
	v_mfma_f32_16x16x32_bf16 v[94:97], v[148:151], v[196:199], v[94:97]
	v_mfma_f32_16x16x32_bf16 v[90:93], v[156:159], v[196:199], v[90:93]
	v_mfma_f32_16x16x32_bf16 v[78:81], v[148:151], v[204:207], v[78:81]
	v_mfma_f32_16x16x32_bf16 v[74:77], v[156:159], v[204:207], v[74:77]
	v_mfma_f32_16x16x32_bf16 v[126:129], v[152:155], v[184:187], v[126:129]
	v_mfma_f32_16x16x32_bf16 v[122:125], v[160:163], v[184:187], v[122:125]
	v_mfma_f32_16x16x32_bf16 v[110:113], v[152:155], v[192:195], v[110:113]
	v_mfma_f32_16x16x32_bf16 v[106:109], v[160:163], v[192:195], v[106:109]
	v_mfma_f32_16x16x32_bf16 v[94:97], v[152:155], v[200:203], v[94:97]
	v_mfma_f32_16x16x32_bf16 v[90:93], v[160:163], v[200:203], v[90:93]
	v_mfma_f32_16x16x32_bf16 v[78:81], v[152:155], v[220:223], v[78:81]
	v_mfma_f32_16x16x32_bf16 v[74:77], v[160:163], v[220:223], v[74:77]
	v_mfma_f32_16x16x32_bf16 v[118:121], v[164:167], v[180:183], v[118:121]
	v_mfma_f32_16x16x32_bf16 v[114:117], v[172:175], v[180:183], v[114:117]
	v_mfma_f32_16x16x32_bf16 v[102:105], v[164:167], v[188:191], v[102:105]
	v_mfma_f32_16x16x32_bf16 v[98:101], v[172:175], v[188:191], v[98:101]
	v_mfma_f32_16x16x32_bf16 v[86:89], v[164:167], v[196:199], v[86:89]
	v_mfma_f32_16x16x32_bf16 v[82:85], v[172:175], v[196:199], v[82:85]
	v_mfma_f32_16x16x32_bf16 v[70:73], v[164:167], v[204:207], v[70:73]
	v_mfma_f32_16x16x32_bf16 v[66:69], v[172:175], v[204:207], v[66:69]
	v_mfma_f32_16x16x32_bf16 v[118:121], v[168:171], v[184:187], v[118:121]
	v_mfma_f32_16x16x32_bf16 v[114:117], v[176:179], v[184:187], v[114:117]
	v_mfma_f32_16x16x32_bf16 v[102:105], v[168:171], v[192:195], v[102:105]
	v_mfma_f32_16x16x32_bf16 v[98:101], v[176:179], v[192:195], v[98:101]
	v_mfma_f32_16x16x32_bf16 v[86:89], v[168:171], v[200:203], v[86:89]
	v_mfma_f32_16x16x32_bf16 v[82:85], v[176:179], v[200:203], v[82:85]
	v_mfma_f32_16x16x32_bf16 v[70:73], v[168:171], v[220:223], v[70:73]
	v_mfma_f32_16x16x32_bf16 v[66:69], v[176:179], v[220:223], v[66:69]
	s_barrier
	s_add_i32 s31, s31, s47
	v_lshl_add_u64 v[208:209], v[208:209], 0, s[96:97]
	s_mov_b32 m0, s31
	ds_read_b128 v[180:183], v147 offset:49152
	ds_read_b128 v[184:187], v147 offset:50176
	ds_read_b128 v[188:191], v147 offset:51200
	ds_read_b128 v[192:195], v147 offset:52224
	ds_read_b128 v[196:199], v147 offset:53248
	ds_read_b128 v[200:203], v147 offset:54272
	ds_read_b128 v[204:207], v147 offset:55296
	ds_read_b128 v[220:223], v147 offset:56320
	global_load_lds_dwordx4 v[208:209], off
	v_lshl_add_u64 v[208:209], v[224:225], 0, s[96:97]
	s_add_i32 m0, s31, 0x2000
	s_add_i32 s31, s64, s47
	global_load_lds_dwordx4 v[208:209], off
	v_lshl_add_u64 v[208:209], v[230:231], 0, s[96:97]
	s_mov_b32 m0, s31
	s_nop 0
	global_load_lds_dwordx4 v[208:209], off
	v_lshl_add_u64 v[208:209], v[236:237], 0, s[96:97]
	s_add_i32 m0, s31, 0x2000
	s_nop 0
	global_load_lds_dwordx4 v[208:209], off
	v_lshl_add_u64 v[208:209], v[238:239], 0, s[96:97]
	s_mov_b32 m0, s57
	s_nop 0
	global_load_lds_dwordx4 v[208:209], off
	v_lshl_add_u64 v[208:209], v[240:241], 0, s[96:97]
	s_mov_b32 m0, s58
	s_nop 0
	global_load_lds_dwordx4 v[208:209], off
	s_nop 0
	s_nop 0
	s_nop 0
	s_nop 0
	s_nop 0
	s_waitcnt vmcnt(8)
	s_waitcnt lgkmcnt(0)
	s_barrier
	s_waitcnt lgkmcnt(0)
	v_mfma_f32_16x16x32_bf16 v[62:65], v[148:151], v[180:183], v[62:65]
	v_mfma_f32_16x16x32_bf16 v[58:61], v[156:159], v[180:183], v[58:61]
	v_mfma_f32_16x16x32_bf16 v[46:49], v[148:151], v[188:191], v[46:49]
	v_mfma_f32_16x16x32_bf16 v[42:45], v[156:159], v[188:191], v[42:45]
	v_mfma_f32_16x16x32_bf16 v[30:33], v[148:151], v[196:199], v[30:33]
	v_mfma_f32_16x16x32_bf16 v[26:29], v[156:159], v[196:199], v[26:29]
	v_mfma_f32_16x16x32_bf16 v[14:17], v[148:151], v[204:207], v[14:17]
	v_mfma_f32_16x16x32_bf16 v[10:13], v[156:159], v[204:207], v[10:13]
	v_mfma_f32_16x16x32_bf16 v[62:65], v[152:155], v[184:187], v[62:65]
	v_mfma_f32_16x16x32_bf16 v[58:61], v[160:163], v[184:187], v[58:61]
	v_mfma_f32_16x16x32_bf16 v[46:49], v[152:155], v[192:195], v[46:49]
	v_mfma_f32_16x16x32_bf16 v[42:45], v[160:163], v[192:195], v[42:45]
	v_mfma_f32_16x16x32_bf16 v[30:33], v[152:155], v[200:203], v[30:33]
	v_mfma_f32_16x16x32_bf16 v[26:29], v[160:163], v[200:203], v[26:29]
	v_mfma_f32_16x16x32_bf16 v[14:17], v[152:155], v[220:223], v[14:17]
	v_mfma_f32_16x16x32_bf16 v[10:13], v[160:163], v[220:223], v[10:13]
	v_mfma_f32_16x16x32_bf16 v[54:57], v[164:167], v[180:183], v[54:57]
	v_mfma_f32_16x16x32_bf16 v[50:53], v[172:175], v[180:183], v[50:53]
	v_mfma_f32_16x16x32_bf16 v[38:41], v[164:167], v[188:191], v[38:41]
	v_mfma_f32_16x16x32_bf16 v[34:37], v[172:175], v[188:191], v[34:37]
	v_mfma_f32_16x16x32_bf16 v[22:25], v[164:167], v[196:199], v[22:25]
	v_mfma_f32_16x16x32_bf16 v[18:21], v[172:175], v[196:199], v[18:21]
	v_mfma_f32_16x16x32_bf16 v[6:9], v[164:167], v[204:207], v[6:9]
	v_mfma_f32_16x16x32_bf16 v[2:5], v[172:175], v[204:207], v[2:5]
	v_mfma_f32_16x16x32_bf16 v[54:57], v[168:171], v[184:187], v[54:57]
	v_mfma_f32_16x16x32_bf16 v[50:53], v[176:179], v[184:187], v[50:53]
	v_mfma_f32_16x16x32_bf16 v[38:41], v[168:171], v[192:195], v[38:41]
	v_mfma_f32_16x16x32_bf16 v[34:37], v[176:179], v[192:195], v[34:37]
	v_mfma_f32_16x16x32_bf16 v[22:25], v[168:171], v[200:203], v[22:25]
	v_mfma_f32_16x16x32_bf16 v[18:21], v[176:179], v[200:203], v[18:21]
	v_mfma_f32_16x16x32_bf16 v[6:9], v[168:171], v[220:223], v[6:9]
	v_mfma_f32_16x16x32_bf16 v[2:5], v[176:179], v[220:223], v[2:5]
	s_barrier
	s_add_u32 s36, s36, 0x100
	s_addc_u32 s37, s37, 0
	v_lshl_add_u64 v[144:145], v[144:145], 0, s[2:3]
	v_lshl_add_u64 v[142:143], v[142:143], 0, s[2:3]
	s_cmp_ge_u32 s63, s56
	s_mov_b32 s31, s63
	s_cbranch_scc0 .LBB0_476
	s_and_b64 vcc, exec, s[6:7]
	s_cbranch_vccnz .LBB0_464
	v_mov_b32_e32 v2, 0
	s_mov_b32 s55, s61
	s_mov_b32 s50, s62
	s_mov_b64 s[26:27], s[34:35]
	s_mov_b64 s[28:29], s[8:9]
	s_mov_b32 s60, s30
	v_mov_b32_e32 v3, v2
	v_mov_b32_e32 v4, v2
	v_mov_b32_e32 v5, v2
	v_mov_b32_e32 v6, v2
	v_mov_b32_e32 v7, v2
	v_mov_b32_e32 v8, v2
	v_mov_b32_e32 v9, v2
	v_mov_b32_e32 v18, v2
	v_mov_b32_e32 v19, v2
	v_mov_b32_e32 v20, v2
	v_mov_b32_e32 v21, v2
	v_mov_b32_e32 v22, v2
	v_mov_b32_e32 v23, v2
	v_mov_b32_e32 v24, v2
	v_mov_b32_e32 v25, v2
	v_mov_b32_e32 v34, v2
	v_mov_b32_e32 v35, v2
	v_mov_b32_e32 v36, v2
	v_mov_b32_e32 v37, v2
	v_mov_b32_e32 v38, v2
	v_mov_b32_e32 v39, v2
	v_mov_b32_e32 v40, v2
	v_mov_b32_e32 v41, v2
	v_mov_b32_e32 v50, v2
	v_mov_b32_e32 v51, v2
	v_mov_b32_e32 v52, v2
	v_mov_b32_e32 v53, v2
	v_mov_b32_e32 v54, v2
	v_mov_b32_e32 v55, v2
	v_mov_b32_e32 v56, v2
	v_mov_b32_e32 v57, v2
	v_mov_b32_e32 v10, v2
	v_mov_b32_e32 v11, v2
	v_mov_b32_e32 v12, v2
	v_mov_b32_e32 v13, v2
	v_mov_b32_e32 v14, v2
	v_mov_b32_e32 v15, v2
	v_mov_b32_e32 v16, v2
	v_mov_b32_e32 v17, v2
	v_mov_b32_e32 v26, v2
	v_mov_b32_e32 v27, v2
	v_mov_b32_e32 v28, v2
	v_mov_b32_e32 v29, v2
	v_mov_b32_e32 v30, v2
	v_mov_b32_e32 v31, v2
	v_mov_b32_e32 v32, v2
	v_mov_b32_e32 v33, v2
	v_mov_b32_e32 v42, v2
	v_mov_b32_e32 v43, v2
	v_mov_b32_e32 v44, v2
	v_mov_b32_e32 v45, v2
	v_mov_b32_e32 v46, v2
	v_mov_b32_e32 v47, v2
	v_mov_b32_e32 v48, v2
	v_mov_b32_e32 v49, v2
	v_mov_b32_e32 v58, v2
	v_mov_b32_e32 v59, v2
	v_mov_b32_e32 v60, v2
	v_mov_b32_e32 v61, v2
	v_mov_b32_e32 v62, v2
	v_mov_b32_e32 v63, v2
	v_mov_b32_e32 v64, v2
	v_mov_b32_e32 v65, v2
	v_mov_b32_e32 v66, v2
	v_mov_b32_e32 v67, v2
	v_mov_b32_e32 v68, v2
	v_mov_b32_e32 v69, v2
	v_mov_b32_e32 v70, v2
	v_mov_b32_e32 v71, v2
	v_mov_b32_e32 v72, v2
	v_mov_b32_e32 v73, v2
	v_mov_b32_e32 v82, v2
	v_mov_b32_e32 v83, v2
	v_mov_b32_e32 v84, v2
	v_mov_b32_e32 v85, v2
	v_mov_b32_e32 v86, v2
	v_mov_b32_e32 v87, v2
	v_mov_b32_e32 v88, v2
	v_mov_b32_e32 v89, v2
	v_mov_b32_e32 v98, v2
	v_mov_b32_e32 v99, v2
	v_mov_b32_e32 v100, v2
	v_mov_b32_e32 v101, v2
	v_mov_b32_e32 v102, v2
	v_mov_b32_e32 v103, v2
	v_mov_b32_e32 v104, v2
	v_mov_b32_e32 v105, v2
	v_mov_b32_e32 v114, v2
	v_mov_b32_e32 v115, v2
	v_mov_b32_e32 v116, v2
	v_mov_b32_e32 v117, v2
	v_mov_b32_e32 v118, v2
	v_mov_b32_e32 v119, v2
	v_mov_b32_e32 v120, v2
	v_mov_b32_e32 v121, v2
	v_mov_b32_e32 v74, v2
	v_mov_b32_e32 v75, v2
	v_mov_b32_e32 v76, v2
	v_mov_b32_e32 v77, v2
	v_mov_b32_e32 v78, v2
	v_mov_b32_e32 v79, v2
	v_mov_b32_e32 v80, v2
	v_mov_b32_e32 v81, v2
	v_mov_b32_e32 v90, v2
	v_mov_b32_e32 v91, v2
	v_mov_b32_e32 v92, v2
	v_mov_b32_e32 v93, v2
	v_mov_b32_e32 v94, v2
	v_mov_b32_e32 v95, v2
	v_mov_b32_e32 v96, v2
	v_mov_b32_e32 v97, v2
	v_mov_b32_e32 v106, v2
	v_mov_b32_e32 v107, v2
	v_mov_b32_e32 v108, v2
	v_mov_b32_e32 v109, v2
	v_mov_b32_e32 v110, v2
	v_mov_b32_e32 v111, v2
	v_mov_b32_e32 v112, v2
	v_mov_b32_e32 v113, v2
	v_mov_b32_e32 v122, v2
	v_mov_b32_e32 v123, v2
	v_mov_b32_e32 v124, v2
	v_mov_b32_e32 v125, v2
	v_mov_b32_e32 v126, v2
	v_mov_b32_e32 v127, v2
	v_mov_b32_e32 v128, v2
	v_mov_b32_e32 v129, v2
	s_branch .LBB0_464
